# grid barrier: idle wave 2 touches the next GEMM phase's first weight K-tiles (immutable since P0) while the barrier is pending, so the phase prologue's B loads hit L2
# speedup vs baseline: 1.0174x; 1.0001x over previous
; #define GSYNC() xcd_barrier(xbar)
; __global__ void __launch_bounds__(512, 2) fwd_megakernel(Params p) {
;     ...
;     GSYNC();
;     { pg8::Gemm g{(const bf16_t*)(ws + WS_MIX), (const bf16_t*)(ws + WS_WOUT)};
;       pg8::StaticOrder S; S.init(MTOK, DM, G, bx);
;       pg8::EpiRes<false, false, true> E{p.x, nullptr, (bf16_t*)(ws + WS_HB), (float*)(ws + WS_SUMSQ1)};
;       pg8::gemm_phase<pg8::GeoPlain<DM>>(lds, g, S, E); }
.Lea_4:
	s_cmp_eq_u32 s100, 2
	s_cbranch_scc0 .Lepf_4
	v_readlane_b32 s100, v253, 2
	v_readlane_b32 s101, v253, 3
	s_sub_u32 s100, s100, 0x80200
	s_subb_u32 s101, s101, 0
	s_add_u32 s100, s100, 0x900000
	s_addc_u32 s101, s101, 0
	s_lshr_b32 s99, s2, 3
	s_lshl_b32 s99, s99, 6
	v_and_b32_e32 v224, 63, v208
	v_add_u32_e32 v224, s99, v224
	v_lshrrev_b32_e32 v225, 1, v224
	v_and_b32_e32 v224, 1, v224
	v_lshlrev_b32_e32 v224, 7, v224
	v_lshl_add_u32 v224, v225, 11, v224
	global_load_dword v226, v224, s[100:101]

; #define GSYNC() xcd_barrier(xbar)
; __global__ void __launch_bounds__(512, 2) fwd_megakernel(Params p) {
;     ...
;     GSYNC();
;     for (int rep = 0; rep < (PROBE_ID == 6 ? 2 : 1); ++rep) {
;     { pg8::Gemm g{(const bf16_t*)(ws + WS_HB), (const bf16_t*)(ws + WS_WQ)};
;       pg8::StaticOrder S; S.init(MTOK, DM, G, bx);
;       pg8::EpiNorm E{(bf16_t*)(ws + WS_QN), (const float*)(ws + WS_SUMSQ1), p.xq_g, 1.0f / 16.0f, nullptr};
;       pg8::gemm_phase<pg8::GeoPlain<DM>>(lds, g, S, E); }
.Lea_5:
	s_cmp_eq_u32 s100, 2
	s_cbranch_scc0 .Lepf_5
	v_readlane_b32 s100, v253, 2
	v_readlane_b32 s101, v253, 3
	s_sub_u32 s100, s100, 0x80200
	s_subb_u32 s101, s101, 0
	s_add_u32 s100, s100, 0xb00000
	s_addc_u32 s101, s101, 0
	s_lshr_b32 s99, s2, 3
	s_lshl_b32 s99, s99, 6
	v_and_b32_e32 v224, 63, v208
	v_add_u32_e32 v224, s99, v224
	v_lshrrev_b32_e32 v225, 1, v224
	v_and_b32_e32 v224, 1, v224
	v_lshlrev_b32_e32 v224, 7, v224
	v_lshl_add_u32 v224, v225, 11, v224
	global_load_dword v226, v224, s[100:101]

; #define GSYNC() xcd_barrier(xbar)
; __global__ void __launch_bounds__(512, 2) fwd_megakernel(Params p) {
;     ...
;     GSYNC();
;     { pg8::Gemm g{(const bf16_t*)(ws + WS_P), (const bf16_t*)(ws + WS_VWT)};
;       pg8::StaticOrder S; S.init(MTOK, DM, G, bx);
;       pg8::EpiRes<true, false, true> E{(const void*)(ws + WS_HB), nullptr, (bf16_t*)(ws + WS_HB), (float*)(ws + WS_SUMSQ2)};
;       pg8::gemm_phase<pg8::Geo<DM, DM, 4 * DM, 0, 256L * 4 * DM, DM, 5>>(lds, g, S, E); }
.Lea_6:
	s_cmp_eq_u32 s100, 2
	s_cbranch_scc0 .Lepf_6
	v_readlane_b32 s100, v253, 2
	v_readlane_b32 s101, v253, 3
	s_sub_u32 s100, s100, 0x80200
	s_subb_u32 s101, s101, 0
	s_add_u32 s100, s100, 0x1e000000
	s_addc_u32 s101, s101, 0
	s_and_b32 s99, s2, 7
	s_lshr_b32 s99, s99, 1
	s_lshl_b32 s99, s99, 11
	s_add_u32 s100, s100, s99
	s_addc_u32 s101, s101, 0
	s_lshr_b32 s99, s2, 3
	s_lshl_b32 s99, s99, 6
	v_and_b32_e32 v224, 63, v208
	v_add_u32_e32 v224, s99, v224
	v_lshrrev_b32_e32 v225, 1, v224
	v_and_b32_e32 v224, 1, v224
	v_lshlrev_b32_e32 v224, 7, v224
	v_lshl_add_u32 v224, v225, 13, v224
	global_load_dword v226, v224, s[100:101]

; #define GSYNC() xcd_barrier(xbar)
; __global__ void __launch_bounds__(512, 2) fwd_megakernel(Params p) {
;     ...
;     GSYNC();
;     for (int rep = 0; rep < (PROBE_ID == 9 ? 2 : 1); ++rep) {
;     { pg8::Gemm g{(const bf16_t*)(ws + WS_HB), (const bf16_t*)(ws + WS_W1)};
;       pg8::StaticOrder S; S.init(MTOK, FF, G, bx);
;       pg8::EpiBf<FF, 1, true, -1> E{(bf16_t*)(ws + WS_U), (const float*)(ws + WS_SUMSQ2), nullptr};
;       pg8::gemm_phase<pg8::GeoPlain<DM>>(lds, g, S, E); }
.Lea_7:
	s_cmp_eq_u32 s100, 2
	s_cbranch_scc0 .Lepf_7
	v_readlane_b32 s100, v253, 2
	v_readlane_b32 s101, v253, 3
	s_sub_u32 s100, s100, 0x80200
	s_subb_u32 s101, s101, 0
	s_add_u32 s100, s100, 0x1300000
	s_addc_u32 s101, s101, 0
	s_lshr_b32 s99, s2, 3
	s_lshl_b32 s99, s99, 6
	v_and_b32_e32 v224, 63, v208
	v_add_u32_e32 v224, s99, v224
	v_lshrrev_b32_e32 v225, 1, v224
	v_and_b32_e32 v224, 1, v224
	v_lshlrev_b32_e32 v224, 7, v224
	v_lshl_add_u32 v224, v225, 11, v224
	global_load_dword v226, v224, s[100:101]
	v_add_u32_e32 v224, 0x200000, v224
	global_load_dword v226, v224, s[100:101]

; #define GSYNC() xcd_barrier(xbar)
; __global__ void __launch_bounds__(512, 2) fwd_megakernel(Params p) {
;     ...
;     GSYNC();
;     { pg8::Gemm g{(const bf16_t*)(ws + WS_U), (const bf16_t*)(ws + WS_W2)};
;       pg8::StaticOrder S; S.init(MTOK, DM, G, bx);
;       pg8::EpiRes<true, true, false> E{(const void*)(ws + WS_HB), p.out, nullptr, nullptr};
;       pg8::gemm_phase<pg8::GeoPlain<FF>>(lds, g, S, E); }
.Lea_8:
	s_cmp_eq_u32 s100, 2
	s_cbranch_scc0 .Lepf_8
	v_readlane_b32 s100, v253, 2
	v_readlane_b32 s101, v253, 3
	s_sub_u32 s100, s100, 0x80200
	s_subb_u32 s101, s101, 0
	s_add_u32 s100, s100, 0x1b00000
	s_addc_u32 s101, s101, 0
	s_lshr_b32 s99, s2, 3
	s_lshl_b32 s99, s99, 6
	v_and_b32_e32 v224, 63, v208
	v_add_u32_e32 v224, s99, v224
	v_lshrrev_b32_e32 v225, 1, v224
	v_and_b32_e32 v224, 1, v224
	v_lshlrev_b32_e32 v224, 7, v224
	v_lshl_add_u32 v224, v225, 13, v224
	global_load_dword v226, v224, s[100:101]
